# sample attention: two 16-key tiles per iteration (40 loads in flight, second tile staged in free VGPRs), on top of v11 G-prefetch
# baseline (speedup 1.0000x reference)
.Lsattn_pair_chk:
	s_cmp_gt_i32 s16, 56
	s_cbranch_scc1 .LBB0_1322
	s_add_i32 s4, s16, 8
	s_cmp_gt_i32 s4, 56
	s_cbranch_scc1 .LBB0_1320
	s_cmp_eq_u32 s16, 56
	s_cselect_b64 s[12:13], -1, 0
	s_and_b64 s[4:5], s[12:13], exec
	s_cselect_b32 s5, s3, s18
	s_cselect_b32 s4, s1, s17
	v_mov_b32_e32 v50, v29
	v_mov_b32_e32 v51, v28
	v_lshl_add_u64 v[28:29], s[4:5], 0, v[34:35]
	v_lshl_add_u64 v[60:61], v[28:29], 0, v[2:3]
	global_load_dwordx4 v[28:31], v[60:61], off offset:16 nt
	global_load_dwordx4 v[52:55], v[60:61], off nt
	global_load_dwordx4 v[56:59], v[60:61], off offset:144 nt
	s_nop 0
	global_load_dwordx4 v[60:63], v[60:61], off offset:128 nt
	s_cselect_b32 s23, s15, s20
	s_cselect_b32 s22, s14, s19
	v_mov_b32_e32 v45, v3
	v_lshl_add_u64 v[64:65], s[22:23], 0, v[44:45]
	v_lshl_add_u64 v[66:67], v[64:65], 0, v[36:37]
	global_load_dword v45, v[66:67], off nt
	v_lshl_add_u64 v[68:69], v[64:65], 0, v[38:39]
	global_load_dword v72, v[68:69], off nt
	v_lshl_add_u64 v[70:71], v[64:65], 0, v[40:41]
	global_load_dword v73, v[70:71], off nt
	v_lshl_add_u64 v[64:65], v[64:65], 0, v[42:43]
	global_load_dword v74, v[64:65], off nt
	global_load_dword v75, v[66:67], off offset:64 nt
	global_load_dword v76, v[68:69], off offset:64 nt
	global_load_dword v77, v[70:71], off offset:64 nt
	global_load_dword v78, v[64:65], off offset:64 nt
	global_load_dword v79, v[66:67], off offset:128 nt
	global_load_dword v80, v[68:69], off offset:128 nt
	global_load_dword v81, v[70:71], off offset:128 nt
	global_load_dword v82, v[64:65], off offset:128 nt
	s_nop 0
	global_load_dword v66, v[66:67], off offset:192 nt
	s_nop 0
	global_load_dword v67, v[68:69], off offset:192 nt
	s_nop 0
	global_load_dword v68, v[70:71], off offset:192 nt
	s_nop 0
	global_load_dword v64, v[64:65], off offset:192 nt
	s_and_b64 s[48:49], s[12:13], vcc
	s_add_i32 s16, s16, 8
	s_add_u32 s4, s17, 0x80000
	s_addc_u32 s5, s18, 0
	v_lshl_add_u64 v[140:141], s[4:5], 0, v[34:35]
	v_lshl_add_u64 v[140:141], v[140:141], 0, v[2:3]
	global_load_dwordx4 v[100:103], v[140:141], off offset:16 nt
	global_load_dwordx4 v[104:107], v[140:141], off nt
	global_load_dwordx4 v[108:111], v[140:141], off offset:144 nt
	global_load_dwordx4 v[112:115], v[140:141], off offset:128 nt
	s_add_u32 s22, s19, 0x80000
	s_addc_u32 s23, s20, 0
	v_mov_b32_e32 v146, v44
	v_mov_b32_e32 v147, v3
	v_lshl_add_u64 v[142:143], s[22:23], 0, v[146:147]
	v_lshl_add_u64 v[132:133], v[142:143], 0, v[36:37]
	v_lshl_add_u64 v[134:135], v[142:143], 0, v[38:39]
	v_lshl_add_u64 v[136:137], v[142:143], 0, v[40:41]
	v_lshl_add_u64 v[138:139], v[142:143], 0, v[42:43]
	global_load_dword v116, v[132:133], off nt
	global_load_dword v117, v[134:135], off nt
	global_load_dword v118, v[136:137], off nt
	global_load_dword v119, v[138:139], off nt
	global_load_dword v120, v[132:133], off offset:64 nt
	global_load_dword v121, v[134:135], off offset:64 nt
	global_load_dword v122, v[136:137], off offset:64 nt
	global_load_dword v123, v[138:139], off offset:64 nt
	global_load_dword v124, v[132:133], off offset:128 nt
	global_load_dword v125, v[134:135], off offset:128 nt
	global_load_dword v126, v[136:137], off offset:128 nt
	global_load_dword v127, v[138:139], off offset:128 nt
	global_load_dword v128, v[132:133], off offset:192 nt
	global_load_dword v129, v[134:135], off offset:192 nt
	global_load_dword v130, v[136:137], off offset:192 nt
	global_load_dword v131, v[138:139], off offset:192 nt
	s_waitcnt vmcnt(20)
	v_bfe_u32 v65, v52, 16, 1
	v_add3_u32 v52, v52, v65, s47
	v_bfe_u32 v65, v53, 16, 1
	v_lshrrev_b32_e32 v52, 16, v52
	v_add3_u32 v53, v53, v65, s47
	v_and_or_b32 v52, v53, s63, v52
	v_bfe_u32 v53, v54, 16, 1
	v_add3_u32 v53, v54, v53, s47
	v_bfe_u32 v54, v55, 16, 1
	v_lshrrev_b32_e32 v53, 16, v53
	v_add3_u32 v54, v55, v54, s47
	v_and_or_b32 v53, v54, s63, v53
	v_bfe_u32 v54, v28, 16, 1
	v_add3_u32 v28, v28, v54, s47
	v_bfe_u32 v54, v29, 16, 1
	v_lshrrev_b32_e32 v28, 16, v28
	v_add3_u32 v29, v29, v54, s47
	v_and_or_b32 v54, v29, s63, v28
	v_bfe_u32 v28, v30, 16, 1
	v_add3_u32 v28, v30, v28, s47
	v_bfe_u32 v29, v31, 16, 1
	v_lshrrev_b32_e32 v28, 16, v28
	v_add3_u32 v29, v31, v29, s47
	v_and_or_b32 v55, v29, s63, v28
	v_bfe_u32 v28, v60, 16, 1
	v_add3_u32 v28, v60, v28, s47
	v_bfe_u32 v29, v61, 16, 1
	v_lshrrev_b32_e32 v28, 16, v28
	v_add3_u32 v29, v61, v29, s47
	v_and_or_b32 v28, v29, s63, v28
	v_bfe_u32 v29, v62, 16, 1
	v_add3_u32 v29, v62, v29, s47
	v_bfe_u32 v30, v63, 16, 1
	v_lshrrev_b32_e32 v29, 16, v29
	v_add3_u32 v30, v63, v30, s47
	v_and_or_b32 v29, v30, s63, v29
	v_bfe_u32 v30, v56, 16, 1
	v_add3_u32 v30, v56, v30, s47
	v_bfe_u32 v31, v57, 16, 1
	v_lshrrev_b32_e32 v30, 16, v30
	v_add3_u32 v31, v57, v31, s47
	v_and_or_b32 v30, v31, s63, v30
	v_bfe_u32 v31, v58, 16, 1
	v_add3_u32 v31, v58, v31, s47
	v_bfe_u32 v56, v59, 16, 1
	v_lshrrev_b32_e32 v31, 16, v31
	v_add3_u32 v56, v59, v56, s47
	v_and_or_b32 v31, v56, s63, v31
	v_mfma_f32_16x16x32_bf16 v[52:55], v[52:55], v[16:19], 0
	s_nop 0
	v_mfma_f32_16x16x32_bf16 v[28:31], v[28:31], v[20:23], v[52:55]
	s_nop 5
	ds_read_b128 v[52:55], v49
	s_nop 0
	v_cndmask_b32_e64 v29, v29, v29, s[48:49]
	v_cndmask_b32_e64 v30, v30, v30, s[48:49]
	v_add_u32_e32 v49, 0x200, v49
	s_waitcnt lgkmcnt(0)
	v_sub_f32_e32 v52, v33, v52
	v_add_f32_e32 v28, v28, v52
	v_mov_b32_e32 v52, s37
	v_cndmask_b32_e64 v52, v28, v52, s[48:49]
	v_cndmask_b32_e64 v28, v31, v31, s[48:49]
	v_sub_f32_e32 v31, v33, v53
	v_add_f32_e32 v29, v31, v29
	s_and_b64 s[48:49], s[12:13], s[40:41]
	v_sub_f32_e32 v31, v33, v54
	v_cndmask_b32_e64 v29, v29, v252, s[48:49]
	v_add_f32_e32 v30, v31, v30
	s_and_b64 s[48:49], s[12:13], s[42:43]
	v_sub_f32_e32 v31, v33, v55
	v_cndmask_b32_e64 v30, v30, v252, s[48:49]
	v_add_f32_e32 v28, v31, v28
	s_and_b64 s[48:49], s[12:13], s[44:45]
	v_cndmask_b32_e64 v31, v28, v252, s[48:49]
	v_max_f32_e32 v28, v31, v31
	v_max_f32_e32 v53, v30, v30
	v_max_f32_e32 v28, v53, v28
	v_max3_f32 v28, v52, v29, v28
	v_mov_b32_e32 v53, v28
	s_nop 1
	v_permlane16_swap_b32_e32 v28, v53
	v_max_f32_e32 v53, v53, v53
	v_max_f32_e32 v28, v28, v28
	v_max_f32_e32 v28, v28, v53
	v_mov_b32_e32 v53, v28
	s_nop 1
	v_permlane32_swap_b32_e32 v28, v53
	v_max3_f32 v28, v51, v28, v53
	v_sub_f32_e32 v30, v30, v28
	v_exp_f32_e32 v57, v30
	v_sub_f32_e32 v30, v31, v28
	v_exp_f32_e32 v31, v30
	v_sub_f32_e32 v29, v29, v28
	v_sub_f32_e32 v52, v52, v28
	v_exp_f32_e32 v29, v29
	v_sub_f32_e32 v51, v51, v28
	v_exp_f32_e32 v56, v52
	v_and_b32_sdwa v53, v31, v253 dst_sel:DWORD dst_unused:UNUSED_PAD src0_sel:WORD_1 src1_sel:DWORD
	v_exp_f32_e32 v30, v51
	v_and_b32_sdwa v51, v57, v253 dst_sel:DWORD dst_unused:UNUSED_PAD src0_sel:WORD_1 src1_sel:DWORD
	v_add3_u32 v53, v31, v53, s47
	v_add3_u32 v51, v57, v51, s47
	v_and_b32_e32 v53, 0xffff0000, v53
	v_and_b32_sdwa v54, v29, v253 dst_sel:DWORD dst_unused:UNUSED_PAD src0_sel:WORD_1 src1_sel:DWORD
	v_or_b32_sdwa v53, v53, v51 dst_sel:DWORD dst_unused:UNUSED_PAD src0_sel:DWORD src1_sel:WORD_1
	v_bfe_u32 v51, v45, 16, 1
	v_and_b32_sdwa v52, v56, v253 dst_sel:DWORD dst_unused:UNUSED_PAD src0_sel:WORD_1 src1_sel:DWORD
	v_add3_u32 v54, v29, v54, s47
	v_add3_u32 v45, v45, v51, s47
	v_bfe_u32 v51, v72, 16, 1
	v_add3_u32 v52, v56, v52, s47
	v_and_b32_e32 v54, 0xffff0000, v54
	v_lshrrev_b32_e32 v45, 16, v45
	v_add3_u32 v51, v72, v51, s47
	v_or_b32_sdwa v52, v54, v52 dst_sel:DWORD dst_unused:UNUSED_PAD src0_sel:DWORD src1_sel:WORD_1
	v_and_or_b32 v54, v51, s63, v45
	v_bfe_u32 v45, v73, 16, 1
	v_add3_u32 v45, v73, v45, s47
	v_bfe_u32 v51, v74, 16, 1
	v_lshrrev_b32_e32 v45, 16, v45
	v_add3_u32 v51, v74, v51, s47
	v_and_or_b32 v55, v51, s63, v45
	v_bfe_u32 v45, v75, 16, 1
	v_add3_u32 v45, v75, v45, s47
	v_bfe_u32 v51, v76, 16, 1
	v_pk_mul_f32 v[26:27], v[26:27], v[30:31] op_sel_hi:[1,0]
	v_pk_mul_f32 v[24:25], v[24:25], v[30:31] op_sel_hi:[1,0]
	v_lshrrev_b32_e32 v45, 16, v45
	v_add3_u32 v51, v76, v51, s47
	v_mfma_f32_16x16x16_bf16 v[24:27], v[54:55], v[52:53], v[24:27]
	v_and_or_b32 v54, v51, s63, v45
	v_bfe_u32 v45, v77, 16, 1
	v_add3_u32 v45, v77, v45, s47
	v_bfe_u32 v51, v78, 16, 1
	v_lshrrev_b32_e32 v45, 16, v45
	v_add3_u32 v51, v78, v51, s47
	v_and_or_b32 v55, v51, s63, v45
	v_bfe_u32 v45, v79, 16, 1
	v_add3_u32 v45, v79, v45, s47
	v_bfe_u32 v51, v80, 16, 1
	v_pk_mul_f32 v[14:15], v[14:15], v[30:31] op_sel_hi:[1,0]
	v_pk_mul_f32 v[12:13], v[12:13], v[30:31] op_sel_hi:[1,0]
	v_lshrrev_b32_e32 v45, 16, v45
	v_add3_u32 v51, v80, v51, s47
	v_mfma_f32_16x16x16_bf16 v[12:15], v[54:55], v[52:53], v[12:15]
	v_and_or_b32 v54, v51, s63, v45
	v_bfe_u32 v45, v81, 16, 1
	v_add3_u32 v45, v81, v45, s47
	v_bfe_u32 v51, v82, 16, 1
	v_lshrrev_b32_e32 v45, 16, v45
	v_add3_u32 v51, v82, v51, s47
	v_and_or_b32 v55, v51, s63, v45
	v_bfe_u32 v45, v66, 16, 1
	v_add3_u32 v45, v66, v45, s47
	v_bfe_u32 v51, v67, 16, 1
	v_pk_mul_f32 v[10:11], v[10:11], v[30:31] op_sel_hi:[1,0]
	v_pk_mul_f32 v[8:9], v[8:9], v[30:31] op_sel_hi:[1,0]
	v_lshrrev_b32_e32 v45, 16, v45
	v_add3_u32 v51, v67, v51, s47
	v_mfma_f32_16x16x16_bf16 v[8:11], v[54:55], v[52:53], v[8:11]
	v_and_or_b32 v54, v51, s63, v45
	v_bfe_u32 v45, v68, 16, 1
	v_add3_u32 v45, v68, v45, s47
	v_bfe_u32 v51, v64, 16, 1
	v_lshrrev_b32_e32 v45, 16, v45
	v_add3_u32 v51, v64, v51, s47
	v_and_or_b32 v55, v51, s63, v45
	v_pk_mul_f32 v[6:7], v[6:7], v[30:31] op_sel_hi:[1,0]
	v_pk_mul_f32 v[4:5], v[4:5], v[30:31] op_sel_hi:[1,0]
	v_add_f32_e32 v45, 0, v56
	s_add_u32 s17, s17, 0x80000
	v_mfma_f32_16x16x16_bf16 v[4:7], v[54:55], v[52:53], v[4:7]
	v_add_f32_e32 v29, v29, v45
	s_addc_u32 s18, s18, 0
	v_add_f32_e32 v29, v57, v29
	s_add_u32 s19, s19, 0x80000
	v_add_f32_e32 v29, v31, v29
	s_addc_u32 s20, s20, 0
	v_fmac_f32_e32 v29, v50, v30
	v_mov_b32_e32 v50, v29
	v_mov_b32_e32 v51, v28
	s_mov_b64 s[12:13], 0
	s_mov_b64 s[48:49], 0
	s_add_i32 s16, s16, 8
	s_waitcnt vmcnt(0)
	v_mov_b32_e32 v28, v100
	v_mov_b32_e32 v29, v101
	v_mov_b32_e32 v30, v102
	v_mov_b32_e32 v31, v103
	v_mov_b32_e32 v52, v104
	v_mov_b32_e32 v53, v105
	v_mov_b32_e32 v54, v106
	v_mov_b32_e32 v55, v107
	v_mov_b32_e32 v56, v108
	v_mov_b32_e32 v57, v109
	v_mov_b32_e32 v58, v110
	v_mov_b32_e32 v59, v111
	v_mov_b32_e32 v60, v112
	v_mov_b32_e32 v61, v113
	v_mov_b32_e32 v62, v114
	v_mov_b32_e32 v63, v115
	v_mov_b32_e32 v45, v116
	v_mov_b32_e32 v72, v117
	v_mov_b32_e32 v73, v118
	v_mov_b32_e32 v74, v119
	v_mov_b32_e32 v75, v120
	v_mov_b32_e32 v76, v121
	v_mov_b32_e32 v77, v122
	v_mov_b32_e32 v78, v123
	v_mov_b32_e32 v79, v124
	v_mov_b32_e32 v80, v125
	v_mov_b32_e32 v81, v126
	v_mov_b32_e32 v82, v127
	v_mov_b32_e32 v66, v128
	v_mov_b32_e32 v67, v129
	v_mov_b32_e32 v68, v130
	v_mov_b32_e32 v64, v131
	v_bfe_u32 v65, v52, 16, 1
	v_add3_u32 v52, v52, v65, s47
	v_bfe_u32 v65, v53, 16, 1
	v_lshrrev_b32_e32 v52, 16, v52
	v_add3_u32 v53, v53, v65, s47
	v_and_or_b32 v52, v53, s63, v52
	v_bfe_u32 v53, v54, 16, 1
	v_add3_u32 v53, v54, v53, s47
	v_bfe_u32 v54, v55, 16, 1
	v_lshrrev_b32_e32 v53, 16, v53
	v_add3_u32 v54, v55, v54, s47
	v_and_or_b32 v53, v54, s63, v53
	v_bfe_u32 v54, v28, 16, 1
	v_add3_u32 v28, v28, v54, s47
	v_bfe_u32 v54, v29, 16, 1
	v_lshrrev_b32_e32 v28, 16, v28
	v_add3_u32 v29, v29, v54, s47
	v_and_or_b32 v54, v29, s63, v28
	v_bfe_u32 v28, v30, 16, 1
	v_add3_u32 v28, v30, v28, s47
	v_bfe_u32 v29, v31, 16, 1
	v_lshrrev_b32_e32 v28, 16, v28
	v_add3_u32 v29, v31, v29, s47
	v_and_or_b32 v55, v29, s63, v28
	v_bfe_u32 v28, v60, 16, 1
	v_add3_u32 v28, v60, v28, s47
	v_bfe_u32 v29, v61, 16, 1
	v_lshrrev_b32_e32 v28, 16, v28
	v_add3_u32 v29, v61, v29, s47
	v_and_or_b32 v28, v29, s63, v28
	v_bfe_u32 v29, v62, 16, 1
	v_add3_u32 v29, v62, v29, s47
	v_bfe_u32 v30, v63, 16, 1
	v_lshrrev_b32_e32 v29, 16, v29
	v_add3_u32 v30, v63, v30, s47
	v_and_or_b32 v29, v30, s63, v29
	v_bfe_u32 v30, v56, 16, 1
	v_add3_u32 v30, v56, v30, s47
	v_bfe_u32 v31, v57, 16, 1
	v_lshrrev_b32_e32 v30, 16, v30
	v_add3_u32 v31, v57, v31, s47
	v_and_or_b32 v30, v31, s63, v30
	v_bfe_u32 v31, v58, 16, 1
	v_add3_u32 v31, v58, v31, s47
	v_bfe_u32 v56, v59, 16, 1
	v_lshrrev_b32_e32 v31, 16, v31
	v_add3_u32 v56, v59, v56, s47
	v_and_or_b32 v31, v56, s63, v31
	v_mfma_f32_16x16x32_bf16 v[52:55], v[52:55], v[16:19], 0
	s_nop 0
	v_mfma_f32_16x16x32_bf16 v[28:31], v[28:31], v[20:23], v[52:55]
	s_nop 5
	ds_read_b128 v[52:55], v49
	s_nop 0
	v_cndmask_b32_e64 v29, v29, v29, s[48:49]
	v_cndmask_b32_e64 v30, v30, v30, s[48:49]
	v_add_u32_e32 v49, 0x200, v49
	s_waitcnt lgkmcnt(0)
	v_sub_f32_e32 v52, v33, v52
	v_add_f32_e32 v28, v28, v52
	v_mov_b32_e32 v52, s37
	v_cndmask_b32_e64 v52, v28, v52, s[48:49]
	v_cndmask_b32_e64 v28, v31, v31, s[48:49]
	v_sub_f32_e32 v31, v33, v53
	v_add_f32_e32 v29, v31, v29
	s_and_b64 s[48:49], s[12:13], s[40:41]
	v_sub_f32_e32 v31, v33, v54
	v_cndmask_b32_e64 v29, v29, v252, s[48:49]
	v_add_f32_e32 v30, v31, v30
	s_and_b64 s[48:49], s[12:13], s[42:43]
	v_sub_f32_e32 v31, v33, v55
	v_cndmask_b32_e64 v30, v30, v252, s[48:49]
	v_add_f32_e32 v28, v31, v28
	s_and_b64 s[48:49], s[12:13], s[44:45]
	v_cndmask_b32_e64 v31, v28, v252, s[48:49]
	v_max_f32_e32 v28, v31, v31
	v_max_f32_e32 v53, v30, v30
	v_max_f32_e32 v28, v53, v28
	v_max3_f32 v28, v52, v29, v28
	v_mov_b32_e32 v53, v28
	s_nop 1
	v_permlane16_swap_b32_e32 v28, v53
	v_max_f32_e32 v53, v53, v53
	v_max_f32_e32 v28, v28, v28
	v_max_f32_e32 v28, v28, v53
	v_mov_b32_e32 v53, v28
	s_nop 1
	v_permlane32_swap_b32_e32 v28, v53
	v_max3_f32 v28, v51, v28, v53
	v_sub_f32_e32 v30, v30, v28
	v_exp_f32_e32 v57, v30
	v_sub_f32_e32 v30, v31, v28
	v_exp_f32_e32 v31, v30
	v_sub_f32_e32 v29, v29, v28
	v_sub_f32_e32 v52, v52, v28
	v_exp_f32_e32 v29, v29
	v_sub_f32_e32 v51, v51, v28
	v_exp_f32_e32 v56, v52
	v_and_b32_sdwa v53, v31, v253 dst_sel:DWORD dst_unused:UNUSED_PAD src0_sel:WORD_1 src1_sel:DWORD
	v_exp_f32_e32 v30, v51
	v_and_b32_sdwa v51, v57, v253 dst_sel:DWORD dst_unused:UNUSED_PAD src0_sel:WORD_1 src1_sel:DWORD
	v_add3_u32 v53, v31, v53, s47
	v_add3_u32 v51, v57, v51, s47
	v_and_b32_e32 v53, 0xffff0000, v53
	v_and_b32_sdwa v54, v29, v253 dst_sel:DWORD dst_unused:UNUSED_PAD src0_sel:WORD_1 src1_sel:DWORD
	v_or_b32_sdwa v53, v53, v51 dst_sel:DWORD dst_unused:UNUSED_PAD src0_sel:DWORD src1_sel:WORD_1
	v_bfe_u32 v51, v45, 16, 1
	v_and_b32_sdwa v52, v56, v253 dst_sel:DWORD dst_unused:UNUSED_PAD src0_sel:WORD_1 src1_sel:DWORD
	v_add3_u32 v54, v29, v54, s47
	v_add3_u32 v45, v45, v51, s47
	v_bfe_u32 v51, v72, 16, 1
	v_add3_u32 v52, v56, v52, s47
	v_and_b32_e32 v54, 0xffff0000, v54
	v_lshrrev_b32_e32 v45, 16, v45
	v_add3_u32 v51, v72, v51, s47
	v_or_b32_sdwa v52, v54, v52 dst_sel:DWORD dst_unused:UNUSED_PAD src0_sel:DWORD src1_sel:WORD_1
	v_and_or_b32 v54, v51, s63, v45
	v_bfe_u32 v45, v73, 16, 1
	v_add3_u32 v45, v73, v45, s47
	v_bfe_u32 v51, v74, 16, 1
	v_lshrrev_b32_e32 v45, 16, v45
	v_add3_u32 v51, v74, v51, s47
	v_and_or_b32 v55, v51, s63, v45
	v_bfe_u32 v45, v75, 16, 1
	v_add3_u32 v45, v75, v45, s47
	v_bfe_u32 v51, v76, 16, 1
	v_pk_mul_f32 v[26:27], v[26:27], v[30:31] op_sel_hi:[1,0]
	v_pk_mul_f32 v[24:25], v[24:25], v[30:31] op_sel_hi:[1,0]
	v_lshrrev_b32_e32 v45, 16, v45
	v_add3_u32 v51, v76, v51, s47
	v_mfma_f32_16x16x16_bf16 v[24:27], v[54:55], v[52:53], v[24:27]
	v_and_or_b32 v54, v51, s63, v45
	v_bfe_u32 v45, v77, 16, 1
	v_add3_u32 v45, v77, v45, s47
	v_bfe_u32 v51, v78, 16, 1
	v_lshrrev_b32_e32 v45, 16, v45
	v_add3_u32 v51, v78, v51, s47
	v_and_or_b32 v55, v51, s63, v45
	v_bfe_u32 v45, v79, 16, 1
	v_add3_u32 v45, v79, v45, s47
	v_bfe_u32 v51, v80, 16, 1
	v_pk_mul_f32 v[14:15], v[14:15], v[30:31] op_sel_hi:[1,0]
	v_pk_mul_f32 v[12:13], v[12:13], v[30:31] op_sel_hi:[1,0]
	v_lshrrev_b32_e32 v45, 16, v45
	v_add3_u32 v51, v80, v51, s47
	v_mfma_f32_16x16x16_bf16 v[12:15], v[54:55], v[52:53], v[12:15]
	v_and_or_b32 v54, v51, s63, v45
	v_bfe_u32 v45, v81, 16, 1
	v_add3_u32 v45, v81, v45, s47
	v_bfe_u32 v51, v82, 16, 1
	v_lshrrev_b32_e32 v45, 16, v45
	v_add3_u32 v51, v82, v51, s47
	v_and_or_b32 v55, v51, s63, v45
	v_bfe_u32 v45, v66, 16, 1
	v_add3_u32 v45, v66, v45, s47
	v_bfe_u32 v51, v67, 16, 1
	v_pk_mul_f32 v[10:11], v[10:11], v[30:31] op_sel_hi:[1,0]
	v_pk_mul_f32 v[8:9], v[8:9], v[30:31] op_sel_hi:[1,0]
	v_lshrrev_b32_e32 v45, 16, v45
	v_add3_u32 v51, v67, v51, s47
	v_mfma_f32_16x16x16_bf16 v[8:11], v[54:55], v[52:53], v[8:11]
	v_and_or_b32 v54, v51, s63, v45
	v_bfe_u32 v45, v68, 16, 1
	v_add3_u32 v45, v68, v45, s47
	v_bfe_u32 v51, v64, 16, 1
	v_lshrrev_b32_e32 v45, 16, v45
	v_add3_u32 v51, v64, v51, s47
	v_and_or_b32 v55, v51, s63, v45
	v_pk_mul_f32 v[6:7], v[6:7], v[30:31] op_sel_hi:[1,0]
	v_pk_mul_f32 v[4:5], v[4:5], v[30:31] op_sel_hi:[1,0]
	v_add_f32_e32 v45, 0, v56
	s_add_u32 s17, s17, 0x80000
	v_mfma_f32_16x16x16_bf16 v[4:7], v[54:55], v[52:53], v[4:7]
	v_add_f32_e32 v29, v29, v45
	s_addc_u32 s18, s18, 0
	v_add_f32_e32 v29, v57, v29
	s_add_u32 s19, s19, 0x80000
	v_add_f32_e32 v29, v31, v29
	s_addc_u32 s20, s20, 0
	v_fmac_f32_e32 v29, v50, v30
	s_branch .Lsattn_pair_chk
